# v20
# baseline (speedup 1.0000x reference)
.LBB0_947:
	v_readlane_b32 s4, v255, 2
	v_readlane_b32 s5, v255, 3
	s_lshl_b64 s[4:5], s[4:5], 2
	s_add_u32 s4, s88, s4
	s_addc_u32 s5, s89, s5
	s_add_u32 s10, s4, 0xc418000
	s_addc_u32 s11, s5, 0
	s_add_u32 s20, s88, 0x1bedb700
	s_addc_u32 s21, s89, 0
	s_add_u32 s22, s88, 0x1fadb700
	s_addc_u32 s23, s89, 0
	s_add_u32 s24, s88, 0x1fcdb700
	s_addc_u32 s25, s89, 0
	s_add_u32 s26, s88, 0x1e6db700
	s_addc_u32 s27, s89, 0
	v_or_b32_e32 v0, s34, v152
	s_add_u32 s28, s88, 0x1f0db700
	v_cmp_eq_u32_e64 s[4:5], 0, v0
	s_addc_u32 s29, s89, 0
	s_waitcnt vmcnt(0) lgkmcnt(0)
	s_barrier
	v_readlane_b32 s100, v255, 8
	s_nop 3
	s_cmp_ge_u32 s100, 4
	s_cbranch_scc1 .Lmy_att_prio
	s_setprio 1
